# packed f32 math in fused epilogue; embedding-projection GEMM moved into the gate GEMM phase (same block re-reads its pp tiles)
# speedup vs baseline: 1.0674x; 1.0070x over previous
; __device__ __forceinline__ int opaque_nblk() { int g = (int)gridDim.x; asm volatile("" : "+s"(g)); return g; }
; __global__ void __launch_bounds__(512, 2) fwd_megakernel(Params Pval) {
;     ...
;             if (sub == 0 || sub == 4 || sub == 6) {
;                 const int ngi = (sub == 0) ? 2 : 1;
;                 for (int gi = 0; gi < ngi; ++gi) {
;                     pg8::Gemm g; EpiAll E{0, layer, ws, P->out};
;                     if (sub == 0 && gi == 0) {
;                         g = pg8::Gemm{(const bf16_t*)(ws + OFF_XB), (const bf16_t*)(ws + OFF_BTIN) + (size_t)layer * NIN * 1024, MTOK, NIN, 1024, 1024};
;                         E.mode = 0;
;                     } else if (sub == 0) {
;                         g = pg8::Gemm{(const bf16_t*)(ws + OFF_PB) + (size_t)layer * MTOK * 256, (const bf16_t*)(ws + OFF_BTP) + (size_t)layer * 1024 * 256, MTOK, 1024, 256, 256};
;                         E.mode = 1;
;                     } else if (sub == 4) {
;                         g = pg8::Gemm{(const bf16_t*)(ws + OFF_PROJ) + COL_Z, (const bf16_t*)(ws + OFF_BTOUT) + (size_t)layer * 1024 * 2048, MTOK, 1024, 2048, PW};
;                         E.mode = 2;
;                     } else {
;                         g = pg8::Gemm{(const bf16_t*)(ws + OFF_PROJ), (const bf16_t*)(ws + OFF_BTG) + (size_t)layer * 1024 * 1024, MTOK, 1024, 1024, 1024};
;                         E.mode = 3;
;                     }
;                     S.init(g.M, g.N, opaque_nblk(), blockIdx.x); pg8::gemm_phase(lds, g, S, E);
.LBB0_96:
	s_cmp_eq_u32 s93, 6
	s_cselect_b32 s1, 1, 0
	s_xor_b32 s3, s76, 1
	s_and_b32 s3, s3, s1
	s_cmp_eq_u32 s3, 0
	s_cselect_b64 s[14:15], -1, 0
	s_mov_b32 s1, 1
	s_cmp_lg_u32 s3, 0
	s_cbranch_scc1 .LBB0_100
	s_cmp_eq_u32 s93, 0
	s_cbranch_scc1 .LBB0_99
	v_readlane_b32 s10, v255, 23
	v_readlane_b32 s12, v255, 27
	v_readlane_b32 s3, v255, 26
	v_readlane_b32 s7, v255, 25
	v_readlane_b32 s11, v255, 24
	v_readlane_b32 s13, v255, 28
	v_readlane_b32 s1, v255, 22
	s_branch .LBB0_101

;     __device__ __forceinline__ void operator()(const f32x4 (&acc)[2][2][4][2], const Unit& u, int wr, int wc, int fr, int fq, const LAS float* rsl) const {
;     ...
;                 } else if (pn < 17) {
;                     f32x4 b0 = acc[ai][0][m][0] * rstd, b1 = acc[ai][0][m][1] * rstd, z0 = acc[ai][1][m][0] * rstd, z1 = acc[ai][1][m][1] * rstd;
; #pragma unroll
;                     for (int j = 0; j < 4; ++j) { float sa, sb; sigmoid2(z0[j], z1[j], sa, sb); b0[j] *= z0[j] * sa; b1[j] *= z1[j] * sb; }
;                     store8bf_nt(rp + COL_BZ + (pn - 9) * 128, b0, b1);
;                 } else if (pn < 25) {
;                     const float r2 = rstd * rstd;
;                     store8bf_nt(rp + COL_HC + (pn - 17) * 128, acc[ai][0][m][0] * acc[ai][1][m][0] * r2, acc[ai][0][m][1] * acc[ai][1][m][1] * r2);
; __device__ void phase_scan_sc(KP P, int layer) {
;     ...
;         for (int i = 0; i < 16; ++i) { float h0[8], bz[8]; bf16_t* bp = proj + (rowS + i) * PW + COL_BZ + ch;
;             unpack8(__builtin_nontemporal_load((const u32x4*)(proj + (rowS + i) * PW + COL_HC + ch)), h0); unpack8(__builtin_nontemporal_load((const u32x4*)bp), bz);
;             float y[8];
; #pragma unroll
;             for (int j = 0; j < 8; ++j) { y[j] = bz[j] * (w0[j] * hm2[j] + w1[j] * hm1[j] + w2[j] * h0[j]); hm2[j] = hm1[j]; hm1[j] = h0[j]; }
;             *(u32x4*)bp = __builtin_bit_cast(u32x4, pack8(y)); }
.Lepi_sc:
	s_waitcnt lgkmcnt(0)
	v_add_u32_e32 v128, s34, v171
	s_lshl_b32 s44, s35, 7
	s_add_i32 s44, s44, 0x1200
	s_add_u32 s44, s98, s44
	s_addc_u32 s45, s99, 0
	v_mov_b32_e32 v206, v227
	v_mov_b32_e32 v207, 0
	v_lshl_add_u64 v[204:205], s[44:45], 0, v[206:207]
	v_mad_i64_i32 v[204:205], s[46:47], v128, s0, v[204:205]
	v_lshlrev_b32_e32 v206, 1, v227
	s_lshl_b32 s44, s35, 8
	s_add_i32 s44, s44, 0x20800
	v_add_u32_e32 v206, s44, v206
	ds_read_b128 v[138:141], v206
	ds_read_b128 v[142:145], v206 offset:4096
	ds_read_b128 v[146:149], v206 offset:8192
	v_and_b32_e32 v234, 15, v212
	v_cmp_gt_u32_e64 s[70:71], 2, v234
	v_cmp_lt_u32_e64 s[72:73], 13, v234
	v_fmamk_f32 v202, v136, 0x3a800000, v209
	v_rsq_f32_e32 v202, v202
	v_pk_mul_f32 v[150:151], v[124:125], v[120:121]
	v_pk_mul_f32 v[152:153], v[126:127], v[122:123]
	v_mul_f32_e32 v206, v202, v202
	v_mul_f32_e32 v234, 0xbfb8aa3b, v202
	v_pk_mul_f32 v[158:159], v[108:109], v[202:203] op_sel_hi:[1,0]
	v_pk_mul_f32 v[160:161], v[110:111], v[202:203] op_sel_hi:[1,0]
	v_pk_mul_f32 v[150:151], v[150:151], v[206:207] op_sel_hi:[1,0]
	v_pk_mul_f32 v[152:153], v[152:153], v[206:207] op_sel_hi:[1,0]
	v_pk_mul_f32 v[162:163], v[108:109], v[234:235] op_sel_hi:[1,0]
	v_pk_mul_f32 v[164:165], v[110:111], v[234:235] op_sel_hi:[1,0]
	v_min_f32_e32 v162, 0x4266d4ca, v162
	v_min_f32_e32 v163, 0x4266d4ca, v163
	v_min_f32_e32 v164, 0x4266d4ca, v164
	v_min_f32_e32 v165, 0x4266d4ca, v165
	v_exp_f32_e32 v162, v162
	v_exp_f32_e32 v163, v163
	v_exp_f32_e32 v164, v164
	v_exp_f32_e32 v165, v165
	s_nop 0
	v_pk_add_f32 v[162:163], v[162:163], 1.0 op_sel_hi:[1,0]
	v_pk_add_f32 v[164:165], v[164:165], 1.0 op_sel_hi:[1,0]
	v_mul_f32_e32 v166, v162, v163
	v_mul_f32_e32 v167, v164, v165
	v_rcp_f32_e32 v166, v166
	v_rcp_f32_e32 v167, v167
	s_nop 0
	v_pk_mul_f32 v[162:163], v[162:163], v[166:167] op_sel:[1,0] op_sel_hi:[0,0]
	v_pk_mul_f32 v[164:165], v[164:165], v[166:167] op_sel:[1,1] op_sel_hi:[0,1]
	v_pk_mul_f32 v[158:159], v[158:159], v[162:163]
	v_pk_mul_f32 v[160:161], v[160:161], v[164:165]
	v_pk_mul_f32 v[162:163], v[116:117], v[202:203] op_sel_hi:[1,0]
	v_pk_mul_f32 v[164:165], v[118:119], v[202:203] op_sel_hi:[1,0]
	v_pk_mul_f32 v[158:159], v[162:163], v[158:159]
	v_pk_mul_f32 v[160:161], v[164:165], v[160:161]
	v_mov_b32_e32 v194, 0
	v_mov_b32_e32 v198, 0
	v_mov_b32_e32 v195, 0
	v_mov_b32_e32 v199, 0
	v_mov_b32_e32 v196, 0
	v_mov_b32_e32 v200, 0
	v_mov_b32_e32 v197, 0
	v_mov_b32_e32 v201, 0
	s_nop 1
	v_mov_b32_dpp v194, v150 row_shr:1 row_mask:0xf bank_mask:0xf
	v_mov_b32_dpp v198, v150 row_shr:2 row_mask:0xf bank_mask:0xf
	v_mov_b32_dpp v195, v151 row_shr:1 row_mask:0xf bank_mask:0xf
	v_mov_b32_dpp v199, v151 row_shr:2 row_mask:0xf bank_mask:0xf
	v_mov_b32_dpp v196, v152 row_shr:1 row_mask:0xf bank_mask:0xf
	v_mov_b32_dpp v200, v152 row_shr:2 row_mask:0xf bank_mask:0xf
	v_mov_b32_dpp v197, v153 row_shr:1 row_mask:0xf bank_mask:0xf
	v_mov_b32_dpp v201, v153 row_shr:2 row_mask:0xf bank_mask:0xf
	s_waitcnt lgkmcnt(0)
	v_pk_mul_f32 v[190:191], v[138:139], v[198:199]
	v_pk_mul_f32 v[192:193], v[140:141], v[200:201]
	v_pk_fma_f32 v[190:191], v[142:143], v[194:195], v[190:191]
	v_pk_fma_f32 v[192:193], v[144:145], v[196:197], v[192:193]
	v_pk_fma_f32 v[190:191], v[146:147], v[150:151], v[190:191]
	v_pk_fma_f32 v[192:193], v[148:149], v[152:153], v[192:193]
	v_pk_mul_f32 v[190:191], v[158:159], v[190:191]
	v_pk_mul_f32 v[192:193], v[160:161], v[192:193]
	v_cndmask_b32_e64 v190, v190, v158, s[70:71]
	v_cndmask_b32_e64 v191, v191, v159, s[70:71]
	v_cndmask_b32_e64 v192, v192, v160, s[70:71]
	v_cndmask_b32_e64 v193, v193, v161, s[70:71]
	v_cvt_pk_bf16_f32 v230, v190, v191
	v_cvt_pk_bf16_f32 v231, v192, v193
	global_store_dwordx2 v[204:205], v[230:231], off
	v_cvt_pk_bf16_f32 v232, v150, v151
	v_cvt_pk_bf16_f32 v233, v152, v153
	s_mov_b64 exec, s[70:71]
	global_store_dwordx2 v[204:205], v[232:233], off offset:2048
	s_mov_b64 exec, -1
	v_add_co_u32_e32 v204, vcc, 0x22000, v204
	s_nop 1
	v_addc_co_u32_e32 v205, vcc, 0, v205, vcc
	v_fmamk_f32 v202, v137, 0x3a800000, v209
	v_rsq_f32_e32 v202, v202
	v_pk_mul_f32 v[154:155], v[112:113], v[104:105]
	v_pk_mul_f32 v[156:157], v[114:115], v[106:107]
	v_mul_f32_e32 v206, v202, v202
	v_mul_f32_e32 v234, 0xbfb8aa3b, v202
	v_pk_mul_f32 v[158:159], v[92:93], v[202:203] op_sel_hi:[1,0]
	v_pk_mul_f32 v[160:161], v[94:95], v[202:203] op_sel_hi:[1,0]
	v_pk_mul_f32 v[154:155], v[154:155], v[206:207] op_sel_hi:[1,0]
	v_pk_mul_f32 v[156:157], v[156:157], v[206:207] op_sel_hi:[1,0]
	v_pk_mul_f32 v[162:163], v[92:93], v[234:235] op_sel_hi:[1,0]
	v_pk_mul_f32 v[164:165], v[94:95], v[234:235] op_sel_hi:[1,0]
	v_min_f32_e32 v162, 0x4266d4ca, v162
	v_min_f32_e32 v163, 0x4266d4ca, v163
	v_min_f32_e32 v164, 0x4266d4ca, v164
	v_min_f32_e32 v165, 0x4266d4ca, v165
	v_exp_f32_e32 v162, v162
	v_exp_f32_e32 v163, v163
	v_exp_f32_e32 v164, v164
	v_exp_f32_e32 v165, v165
	s_nop 0
	v_pk_add_f32 v[162:163], v[162:163], 1.0 op_sel_hi:[1,0]
	v_pk_add_f32 v[164:165], v[164:165], 1.0 op_sel_hi:[1,0]
	v_mul_f32_e32 v166, v162, v163
	v_mul_f32_e32 v167, v164, v165
	v_rcp_f32_e32 v166, v166
	v_rcp_f32_e32 v167, v167
	s_nop 0
	v_pk_mul_f32 v[162:163], v[162:163], v[166:167] op_sel:[1,0] op_sel_hi:[0,0]
	v_pk_mul_f32 v[164:165], v[164:165], v[166:167] op_sel:[1,1] op_sel_hi:[0,1]
	v_pk_mul_f32 v[158:159], v[158:159], v[162:163]
	v_pk_mul_f32 v[160:161], v[160:161], v[164:165]
	v_pk_mul_f32 v[162:163], v[100:101], v[202:203] op_sel_hi:[1,0]
	v_pk_mul_f32 v[164:165], v[102:103], v[202:203] op_sel_hi:[1,0]
	v_pk_mul_f32 v[158:159], v[162:163], v[158:159]
	v_pk_mul_f32 v[160:161], v[164:165], v[160:161]
;     __device__ __forceinline__ void operator()(const f32x4 (&acc)[2][2][4][2], const Unit& u, int wr, int wc, int fr, int fq, const LAS float* rsl) const {
;     ...
;                 } else if (pn < 17) {
;                     f32x4 b0 = acc[ai][0][m][0] * rstd, b1 = acc[ai][0][m][1] * rstd, z0 = acc[ai][1][m][0] * rstd, z1 = acc[ai][1][m][1] * rstd;
; #pragma unroll
;                     for (int j = 0; j < 4; ++j) { float sa, sb; sigmoid2(z0[j], z1[j], sa, sb); b0[j] *= z0[j] * sa; b1[j] *= z1[j] * sb; }
;                     store8bf_nt(rp + COL_BZ + (pn - 9) * 128, b0, b1);
;                 } else if (pn < 25) {
;                     const float r2 = rstd * rstd;
;                     store8bf_nt(rp + COL_HC + (pn - 17) * 128, acc[ai][0][m][0] * acc[ai][1][m][0] * r2, acc[ai][0][m][1] * acc[ai][1][m][1] * r2);
; __device__ void phase_scan_sc(KP P, int layer) {
;     ...
;         for (int i = 0; i < 16; ++i) { float h0[8], bz[8]; bf16_t* bp = proj + (rowS + i) * PW + COL_BZ + ch;
;             unpack8(__builtin_nontemporal_load((const u32x4*)(proj + (rowS + i) * PW + COL_HC + ch)), h0); unpack8(__builtin_nontemporal_load((const u32x4*)bp), bz);
;             float y[8];
; #pragma unroll
;             for (int j = 0; j < 8; ++j) { y[j] = bz[j] * (w0[j] * hm2[j] + w1[j] * hm1[j] + w2[j] * h0[j]); hm2[j] = hm1[j]; hm1[j] = h0[j]; }
;             *(u32x4*)bp = __builtin_bit_cast(u32x4, pack8(y)); }
	v_mov_b32_dpp v194, v150 row_ror:1 row_mask:0xf bank_mask:0xf
	v_mov_b32_dpp v198, v150 row_ror:2 row_mask:0xf bank_mask:0xf
	v_mov_b32_dpp v195, v151 row_ror:1 row_mask:0xf bank_mask:0xf
	v_mov_b32_dpp v199, v151 row_ror:2 row_mask:0xf bank_mask:0xf
	v_mov_b32_dpp v196, v152 row_ror:1 row_mask:0xf bank_mask:0xf
	v_mov_b32_dpp v200, v152 row_ror:2 row_mask:0xf bank_mask:0xf
	v_mov_b32_dpp v197, v153 row_ror:1 row_mask:0xf bank_mask:0xf
	v_mov_b32_dpp v201, v153 row_ror:2 row_mask:0xf bank_mask:0xf
	s_nop 1
	v_mov_b32_dpp v194, v154 row_shr:1 row_mask:0xf bank_mask:0xf
	v_mov_b32_dpp v198, v154 row_shr:2 row_mask:0xf bank_mask:0xf
	v_mov_b32_dpp v195, v155 row_shr:1 row_mask:0xf bank_mask:0xf
	v_mov_b32_dpp v199, v155 row_shr:2 row_mask:0xf bank_mask:0xf
	v_mov_b32_dpp v196, v156 row_shr:1 row_mask:0xf bank_mask:0xf
	v_mov_b32_dpp v200, v156 row_shr:2 row_mask:0xf bank_mask:0xf
	v_mov_b32_dpp v197, v157 row_shr:1 row_mask:0xf bank_mask:0xf
	v_mov_b32_dpp v201, v157 row_shr:2 row_mask:0xf bank_mask:0xf
	v_pk_mul_f32 v[190:191], v[138:139], v[198:199]
	v_pk_mul_f32 v[192:193], v[140:141], v[200:201]
	v_pk_fma_f32 v[190:191], v[142:143], v[194:195], v[190:191]
	v_pk_fma_f32 v[192:193], v[144:145], v[196:197], v[192:193]
	v_pk_fma_f32 v[190:191], v[146:147], v[154:155], v[190:191]
	v_pk_fma_f32 v[192:193], v[148:149], v[156:157], v[192:193]
	v_pk_mul_f32 v[190:191], v[158:159], v[190:191]
	v_pk_mul_f32 v[192:193], v[160:161], v[192:193]
	v_cvt_pk_bf16_f32 v230, v190, v191
	v_cvt_pk_bf16_f32 v231, v192, v193
	global_store_dwordx2 v[204:205], v[230:231], off
	v_add_co_u32_e32 v204, vcc, 0x22000, v204
	s_nop 1
	v_addc_co_u32_e32 v205, vcc, 0, v205, vcc
	v_fmamk_f32 v202, v134, 0x3a800000, v209
	v_rsq_f32_e32 v202, v202
	v_pk_mul_f32 v[150:151], v[96:97], v[88:89]
	v_pk_mul_f32 v[152:153], v[98:99], v[90:91]
	v_mul_f32_e32 v206, v202, v202
	v_mul_f32_e32 v234, 0xbfb8aa3b, v202
	v_pk_mul_f32 v[158:159], v[76:77], v[202:203] op_sel_hi:[1,0]
	v_pk_mul_f32 v[160:161], v[78:79], v[202:203] op_sel_hi:[1,0]
	v_pk_mul_f32 v[150:151], v[150:151], v[206:207] op_sel_hi:[1,0]
	v_pk_mul_f32 v[152:153], v[152:153], v[206:207] op_sel_hi:[1,0]
	v_pk_mul_f32 v[162:163], v[76:77], v[234:235] op_sel_hi:[1,0]
	v_pk_mul_f32 v[164:165], v[78:79], v[234:235] op_sel_hi:[1,0]
	v_min_f32_e32 v162, 0x4266d4ca, v162
	v_min_f32_e32 v163, 0x4266d4ca, v163
	v_min_f32_e32 v164, 0x4266d4ca, v164
	v_min_f32_e32 v165, 0x4266d4ca, v165
	v_exp_f32_e32 v162, v162
	v_exp_f32_e32 v163, v163
	v_exp_f32_e32 v164, v164
	v_exp_f32_e32 v165, v165
	s_nop 0
	v_pk_add_f32 v[162:163], v[162:163], 1.0 op_sel_hi:[1,0]
	v_pk_add_f32 v[164:165], v[164:165], 1.0 op_sel_hi:[1,0]
	v_mul_f32_e32 v166, v162, v163
	v_mul_f32_e32 v167, v164, v165
	v_rcp_f32_e32 v166, v166
	v_rcp_f32_e32 v167, v167
	s_nop 0
	v_pk_mul_f32 v[162:163], v[162:163], v[166:167] op_sel:[1,0] op_sel_hi:[0,0]
	v_pk_mul_f32 v[164:165], v[164:165], v[166:167] op_sel:[1,1] op_sel_hi:[0,1]
	v_pk_mul_f32 v[158:159], v[158:159], v[162:163]
	v_pk_mul_f32 v[160:161], v[160:161], v[164:165]
	v_pk_mul_f32 v[162:163], v[84:85], v[202:203] op_sel_hi:[1,0]
	v_pk_mul_f32 v[164:165], v[86:87], v[202:203] op_sel_hi:[1,0]
	v_pk_mul_f32 v[158:159], v[162:163], v[158:159]
	v_pk_mul_f32 v[160:161], v[164:165], v[160:161]
	v_mov_b32_dpp v194, v154 row_ror:1 row_mask:0xf bank_mask:0xf
	v_mov_b32_dpp v198, v154 row_ror:2 row_mask:0xf bank_mask:0xf
	v_mov_b32_dpp v195, v155 row_ror:1 row_mask:0xf bank_mask:0xf
	v_mov_b32_dpp v199, v155 row_ror:2 row_mask:0xf bank_mask:0xf
	v_mov_b32_dpp v196, v156 row_ror:1 row_mask:0xf bank_mask:0xf
	v_mov_b32_dpp v200, v156 row_ror:2 row_mask:0xf bank_mask:0xf
	v_mov_b32_dpp v197, v157 row_ror:1 row_mask:0xf bank_mask:0xf
	v_mov_b32_dpp v201, v157 row_ror:2 row_mask:0xf bank_mask:0xf
	s_nop 1
	v_mov_b32_dpp v194, v150 row_shr:1 row_mask:0xf bank_mask:0xf
	v_mov_b32_dpp v198, v150 row_shr:2 row_mask:0xf bank_mask:0xf
	v_mov_b32_dpp v195, v151 row_shr:1 row_mask:0xf bank_mask:0xf
	v_mov_b32_dpp v199, v151 row_shr:2 row_mask:0xf bank_mask:0xf
	v_mov_b32_dpp v196, v152 row_shr:1 row_mask:0xf bank_mask:0xf
	v_mov_b32_dpp v200, v152 row_shr:2 row_mask:0xf bank_mask:0xf
	v_mov_b32_dpp v197, v153 row_shr:1 row_mask:0xf bank_mask:0xf
	v_mov_b32_dpp v201, v153 row_shr:2 row_mask:0xf bank_mask:0xf
	v_pk_mul_f32 v[190:191], v[138:139], v[198:199]
	v_pk_mul_f32 v[192:193], v[140:141], v[200:201]
	v_pk_fma_f32 v[190:191], v[142:143], v[194:195], v[190:191]
	v_pk_fma_f32 v[192:193], v[144:145], v[196:197], v[192:193]
	v_pk_fma_f32 v[190:191], v[146:147], v[150:151], v[190:191]
	v_pk_fma_f32 v[192:193], v[148:149], v[152:153], v[192:193]
	v_pk_mul_f32 v[190:191], v[158:159], v[190:191]
	v_pk_mul_f32 v[192:193], v[160:161], v[192:193]
	v_cvt_pk_bf16_f32 v230, v190, v191
	v_cvt_pk_bf16_f32 v231, v192, v193
	global_store_dwordx2 v[204:205], v[230:231], off
	v_add_co_u32_e32 v204, vcc, 0x22000, v204
	s_nop 1
	v_addc_co_u32_e32 v205, vcc, 0, v205, vcc
	v_fmamk_f32 v202, v135, 0x3a800000, v209
	v_rsq_f32_e32 v202, v202
	v_pk_mul_f32 v[154:155], v[80:81], v[72:73]
	v_pk_mul_f32 v[156:157], v[82:83], v[74:75]
	v_mul_f32_e32 v206, v202, v202
	v_mul_f32_e32 v234, 0xbfb8aa3b, v202
	v_pk_mul_f32 v[158:159], v[64:65], v[202:203] op_sel_hi:[1,0]
	v_pk_mul_f32 v[160:161], v[66:67], v[202:203] op_sel_hi:[1,0]
	v_pk_mul_f32 v[154:155], v[154:155], v[206:207] op_sel_hi:[1,0]
	v_pk_mul_f32 v[156:157], v[156:157], v[206:207] op_sel_hi:[1,0]
	v_pk_mul_f32 v[162:163], v[64:65], v[234:235] op_sel_hi:[1,0]
	v_pk_mul_f32 v[164:165], v[66:67], v[234:235] op_sel_hi:[1,0]
	v_min_f32_e32 v162, 0x4266d4ca, v162
	v_min_f32_e32 v163, 0x4266d4ca, v163
;     __device__ __forceinline__ void operator()(const f32x4 (&acc)[2][2][4][2], const Unit& u, int wr, int wc, int fr, int fq, const LAS float* rsl) const {
;     ...
;                 } else if (pn < 17) {
;                     f32x4 b0 = acc[ai][0][m][0] * rstd, b1 = acc[ai][0][m][1] * rstd, z0 = acc[ai][1][m][0] * rstd, z1 = acc[ai][1][m][1] * rstd;
; #pragma unroll
;                     for (int j = 0; j < 4; ++j) { float sa, sb; sigmoid2(z0[j], z1[j], sa, sb); b0[j] *= z0[j] * sa; b1[j] *= z1[j] * sb; }
;                     store8bf_nt(rp + COL_BZ + (pn - 9) * 128, b0, b1);
;                 } else if (pn < 25) {
;                     const float r2 = rstd * rstd;
;                     store8bf_nt(rp + COL_HC + (pn - 17) * 128, acc[ai][0][m][0] * acc[ai][1][m][0] * r2, acc[ai][0][m][1] * acc[ai][1][m][1] * r2);
; __device__ void phase_scan_sc(KP P, int layer) {
;     ...
;         for (int i = 0; i < 16; ++i) { float h0[8], bz[8]; bf16_t* bp = proj + (rowS + i) * PW + COL_BZ + ch;
;             unpack8(__builtin_nontemporal_load((const u32x4*)(proj + (rowS + i) * PW + COL_HC + ch)), h0); unpack8(__builtin_nontemporal_load((const u32x4*)bp), bz);
;             float y[8];
; #pragma unroll
;             for (int j = 0; j < 8; ++j) { y[j] = bz[j] * (w0[j] * hm2[j] + w1[j] * hm1[j] + w2[j] * h0[j]); hm2[j] = hm1[j]; hm1[j] = h0[j]; }
;             *(u32x4*)bp = __builtin_bit_cast(u32x4, pack8(y)); }
	v_min_f32_e32 v164, 0x4266d4ca, v164
	v_min_f32_e32 v165, 0x4266d4ca, v165
	v_exp_f32_e32 v162, v162
	v_exp_f32_e32 v163, v163
	v_exp_f32_e32 v164, v164
	v_exp_f32_e32 v165, v165
	s_nop 0
	v_pk_add_f32 v[162:163], v[162:163], 1.0 op_sel_hi:[1,0]
	v_pk_add_f32 v[164:165], v[164:165], 1.0 op_sel_hi:[1,0]
	v_mul_f32_e32 v166, v162, v163
	v_mul_f32_e32 v167, v164, v165
	v_rcp_f32_e32 v166, v166
	v_rcp_f32_e32 v167, v167
	s_nop 0
	v_pk_mul_f32 v[162:163], v[162:163], v[166:167] op_sel:[1,0] op_sel_hi:[0,0]
	v_pk_mul_f32 v[164:165], v[164:165], v[166:167] op_sel:[1,1] op_sel_hi:[0,1]
	v_pk_mul_f32 v[158:159], v[158:159], v[162:163]
	v_pk_mul_f32 v[160:161], v[160:161], v[164:165]
	v_pk_mul_f32 v[162:163], v[68:69], v[202:203] op_sel_hi:[1,0]
	v_pk_mul_f32 v[164:165], v[70:71], v[202:203] op_sel_hi:[1,0]
	v_pk_mul_f32 v[158:159], v[162:163], v[158:159]
	v_pk_mul_f32 v[160:161], v[164:165], v[160:161]
	v_mov_b32_dpp v194, v150 row_ror:1 row_mask:0xf bank_mask:0xf
	v_mov_b32_dpp v198, v150 row_ror:2 row_mask:0xf bank_mask:0xf
	v_mov_b32_dpp v195, v151 row_ror:1 row_mask:0xf bank_mask:0xf
	v_mov_b32_dpp v199, v151 row_ror:2 row_mask:0xf bank_mask:0xf
	v_mov_b32_dpp v196, v152 row_ror:1 row_mask:0xf bank_mask:0xf
	v_mov_b32_dpp v200, v152 row_ror:2 row_mask:0xf bank_mask:0xf
	v_mov_b32_dpp v197, v153 row_ror:1 row_mask:0xf bank_mask:0xf
	v_mov_b32_dpp v201, v153 row_ror:2 row_mask:0xf bank_mask:0xf
	s_nop 1
	v_mov_b32_dpp v194, v154 row_shr:1 row_mask:0xf bank_mask:0xf
	v_mov_b32_dpp v198, v154 row_shr:2 row_mask:0xf bank_mask:0xf
	v_mov_b32_dpp v195, v155 row_shr:1 row_mask:0xf bank_mask:0xf
	v_mov_b32_dpp v199, v155 row_shr:2 row_mask:0xf bank_mask:0xf
	v_mov_b32_dpp v196, v156 row_shr:1 row_mask:0xf bank_mask:0xf
	v_mov_b32_dpp v200, v156 row_shr:2 row_mask:0xf bank_mask:0xf
	v_mov_b32_dpp v197, v157 row_shr:1 row_mask:0xf bank_mask:0xf
	v_mov_b32_dpp v201, v157 row_shr:2 row_mask:0xf bank_mask:0xf
	v_pk_mul_f32 v[190:191], v[138:139], v[198:199]
	v_pk_mul_f32 v[192:193], v[140:141], v[200:201]
	v_pk_fma_f32 v[190:191], v[142:143], v[194:195], v[190:191]
	v_pk_fma_f32 v[192:193], v[144:145], v[196:197], v[192:193]
	v_pk_fma_f32 v[190:191], v[146:147], v[154:155], v[190:191]
	v_pk_fma_f32 v[192:193], v[148:149], v[156:157], v[192:193]
	v_pk_mul_f32 v[190:191], v[158:159], v[190:191]
	v_pk_mul_f32 v[192:193], v[160:161], v[192:193]
	v_cvt_pk_bf16_f32 v230, v190, v191
	v_cvt_pk_bf16_f32 v231, v192, v193
	global_store_dwordx2 v[204:205], v[230:231], off
	v_cvt_pk_bf16_f32 v232, v154, v155
	v_cvt_pk_bf16_f32 v233, v156, v157
	s_mov_b64 exec, s[72:73]
	global_store_dwordx2 v[204:205], v[232:233], off offset:2048
	s_mov_b64 exec, -1
	v_add_co_u32_e32 v204, vcc, 0xaa000, v204
	s_nop 1
	v_addc_co_u32_e32 v205, vcc, 0, v205, vcc
	v_fmamk_f32 v202, v132, 0x3a800000, v209
	v_rsq_f32_e32 v202, v202
	v_pk_mul_f32 v[150:151], v[60:61], v[56:57]
	v_pk_mul_f32 v[152:153], v[62:63], v[58:59]
	v_mul_f32_e32 v206, v202, v202
	v_mul_f32_e32 v234, 0xbfb8aa3b, v202
	v_pk_mul_f32 v[158:159], v[40:41], v[202:203] op_sel_hi:[1,0]
	v_pk_mul_f32 v[160:161], v[42:43], v[202:203] op_sel_hi:[1,0]
	v_pk_mul_f32 v[150:151], v[150:151], v[206:207] op_sel_hi:[1,0]
	v_pk_mul_f32 v[152:153], v[152:153], v[206:207] op_sel_hi:[1,0]
	v_pk_mul_f32 v[162:163], v[40:41], v[234:235] op_sel_hi:[1,0]
	v_pk_mul_f32 v[164:165], v[42:43], v[234:235] op_sel_hi:[1,0]
	v_min_f32_e32 v162, 0x4266d4ca, v162
	v_min_f32_e32 v163, 0x4266d4ca, v163
	v_min_f32_e32 v164, 0x4266d4ca, v164
	v_min_f32_e32 v165, 0x4266d4ca, v165
	v_exp_f32_e32 v162, v162
	v_exp_f32_e32 v163, v163
	v_exp_f32_e32 v164, v164
	v_exp_f32_e32 v165, v165
	s_nop 0
	v_pk_add_f32 v[162:163], v[162:163], 1.0 op_sel_hi:[1,0]
	v_pk_add_f32 v[164:165], v[164:165], 1.0 op_sel_hi:[1,0]
	v_mul_f32_e32 v166, v162, v163
	v_mul_f32_e32 v167, v164, v165
	v_rcp_f32_e32 v166, v166
	v_rcp_f32_e32 v167, v167
	s_nop 0
	v_pk_mul_f32 v[162:163], v[162:163], v[166:167] op_sel:[1,0] op_sel_hi:[0,0]
	v_pk_mul_f32 v[164:165], v[164:165], v[166:167] op_sel:[1,1] op_sel_hi:[0,1]
	v_pk_mul_f32 v[158:159], v[158:159], v[162:163]
	v_pk_mul_f32 v[160:161], v[160:161], v[164:165]
	v_pk_mul_f32 v[162:163], v[48:49], v[202:203] op_sel_hi:[1,0]
	v_pk_mul_f32 v[164:165], v[50:51], v[202:203] op_sel_hi:[1,0]
	v_pk_mul_f32 v[158:159], v[162:163], v[158:159]
	v_pk_mul_f32 v[160:161], v[164:165], v[160:161]
	v_mov_b32_e32 v194, 0
	v_mov_b32_e32 v198, 0
	v_mov_b32_e32 v195, 0
	v_mov_b32_e32 v199, 0
	v_mov_b32_e32 v196, 0
	v_mov_b32_e32 v200, 0
	v_mov_b32_e32 v197, 0
	v_mov_b32_e32 v201, 0
	s_nop 1
	v_mov_b32_dpp v194, v150 row_shr:1 row_mask:0xf bank_mask:0xf
	v_mov_b32_dpp v198, v150 row_shr:2 row_mask:0xf bank_mask:0xf
	v_mov_b32_dpp v195, v151 row_shr:1 row_mask:0xf bank_mask:0xf
	v_mov_b32_dpp v199, v151 row_shr:2 row_mask:0xf bank_mask:0xf
	v_mov_b32_dpp v196, v152 row_shr:1 row_mask:0xf bank_mask:0xf
	v_mov_b32_dpp v200, v152 row_shr:2 row_mask:0xf bank_mask:0xf
	v_mov_b32_dpp v197, v153 row_shr:1 row_mask:0xf bank_mask:0xf
	v_mov_b32_dpp v201, v153 row_shr:2 row_mask:0xf bank_mask:0xf
	v_pk_mul_f32 v[190:191], v[138:139], v[198:199]
	v_pk_mul_f32 v[192:193], v[140:141], v[200:201]
	v_pk_fma_f32 v[190:191], v[142:143], v[194:195], v[190:191]
	v_pk_fma_f32 v[192:193], v[144:145], v[196:197], v[192:193]
	v_pk_fma_f32 v[190:191], v[146:147], v[150:151], v[190:191]
	v_pk_fma_f32 v[192:193], v[148:149], v[152:153], v[192:193]
	v_pk_mul_f32 v[190:191], v[158:159], v[190:191]
	v_pk_mul_f32 v[192:193], v[160:161], v[192:193]
	v_cndmask_b32_e64 v190, v190, v158, s[70:71]
	v_cndmask_b32_e64 v191, v191, v159, s[70:71]
	v_cndmask_b32_e64 v192, v192, v160, s[70:71]
;     __device__ __forceinline__ void operator()(const f32x4 (&acc)[2][2][4][2], const Unit& u, int wr, int wc, int fr, int fq, const LAS float* rsl) const {
;     ...
;                 } else if (pn < 17) {
;                     f32x4 b0 = acc[ai][0][m][0] * rstd, b1 = acc[ai][0][m][1] * rstd, z0 = acc[ai][1][m][0] * rstd, z1 = acc[ai][1][m][1] * rstd;
; #pragma unroll
;                     for (int j = 0; j < 4; ++j) { float sa, sb; sigmoid2(z0[j], z1[j], sa, sb); b0[j] *= z0[j] * sa; b1[j] *= z1[j] * sb; }
;                     store8bf_nt(rp + COL_BZ + (pn - 9) * 128, b0, b1);
;                 } else if (pn < 25) {
;                     const float r2 = rstd * rstd;
;                     store8bf_nt(rp + COL_HC + (pn - 17) * 128, acc[ai][0][m][0] * acc[ai][1][m][0] * r2, acc[ai][0][m][1] * acc[ai][1][m][1] * r2);
; __device__ void phase_scan_sc(KP P, int layer) {
;     ...
;         for (int i = 0; i < 16; ++i) { float h0[8], bz[8]; bf16_t* bp = proj + (rowS + i) * PW + COL_BZ + ch;
;             unpack8(__builtin_nontemporal_load((const u32x4*)(proj + (rowS + i) * PW + COL_HC + ch)), h0); unpack8(__builtin_nontemporal_load((const u32x4*)bp), bz);
;             float y[8];
; #pragma unroll
;             for (int j = 0; j < 8; ++j) { y[j] = bz[j] * (w0[j] * hm2[j] + w1[j] * hm1[j] + w2[j] * h0[j]); hm2[j] = hm1[j]; hm1[j] = h0[j]; }
;             *(u32x4*)bp = __builtin_bit_cast(u32x4, pack8(y)); }
	v_cndmask_b32_e64 v193, v193, v161, s[70:71]
	v_cvt_pk_bf16_f32 v230, v190, v191
	v_cvt_pk_bf16_f32 v231, v192, v193
	global_store_dwordx2 v[204:205], v[230:231], off
	v_cvt_pk_bf16_f32 v232, v150, v151
	v_cvt_pk_bf16_f32 v233, v152, v153
	s_mov_b64 exec, s[70:71]
	global_store_dwordx2 v[204:205], v[232:233], off offset:2048
	s_mov_b64 exec, -1
	v_add_co_u32_e32 v204, vcc, 0x22000, v204
	s_nop 1
	v_addc_co_u32_e32 v205, vcc, 0, v205, vcc
	v_fmamk_f32 v202, v133, 0x3a800000, v209
	v_rsq_f32_e32 v202, v202
	v_pk_mul_f32 v[154:155], v[52:53], v[44:45]
	v_pk_mul_f32 v[156:157], v[54:55], v[46:47]
	v_mul_f32_e32 v206, v202, v202
	v_mul_f32_e32 v234, 0xbfb8aa3b, v202
	v_pk_mul_f32 v[158:159], v[24:25], v[202:203] op_sel_hi:[1,0]
	v_pk_mul_f32 v[160:161], v[26:27], v[202:203] op_sel_hi:[1,0]
	v_pk_mul_f32 v[154:155], v[154:155], v[206:207] op_sel_hi:[1,0]
	v_pk_mul_f32 v[156:157], v[156:157], v[206:207] op_sel_hi:[1,0]
	v_pk_mul_f32 v[162:163], v[24:25], v[234:235] op_sel_hi:[1,0]
	v_pk_mul_f32 v[164:165], v[26:27], v[234:235] op_sel_hi:[1,0]
	v_min_f32_e32 v162, 0x4266d4ca, v162
	v_min_f32_e32 v163, 0x4266d4ca, v163
	v_min_f32_e32 v164, 0x4266d4ca, v164
	v_min_f32_e32 v165, 0x4266d4ca, v165
	v_exp_f32_e32 v162, v162
	v_exp_f32_e32 v163, v163
	v_exp_f32_e32 v164, v164
	v_exp_f32_e32 v165, v165
	s_nop 0
	v_pk_add_f32 v[162:163], v[162:163], 1.0 op_sel_hi:[1,0]
	v_pk_add_f32 v[164:165], v[164:165], 1.0 op_sel_hi:[1,0]
	v_mul_f32_e32 v166, v162, v163
	v_mul_f32_e32 v167, v164, v165
	v_rcp_f32_e32 v166, v166
	v_rcp_f32_e32 v167, v167
	s_nop 0
	v_pk_mul_f32 v[162:163], v[162:163], v[166:167] op_sel:[1,0] op_sel_hi:[0,0]
	v_pk_mul_f32 v[164:165], v[164:165], v[166:167] op_sel:[1,1] op_sel_hi:[0,1]
	v_pk_mul_f32 v[158:159], v[158:159], v[162:163]
	v_pk_mul_f32 v[160:161], v[160:161], v[164:165]
	v_pk_mul_f32 v[162:163], v[32:33], v[202:203] op_sel_hi:[1,0]
	v_pk_mul_f32 v[164:165], v[34:35], v[202:203] op_sel_hi:[1,0]
	v_pk_mul_f32 v[158:159], v[162:163], v[158:159]
	v_pk_mul_f32 v[160:161], v[164:165], v[160:161]
	v_mov_b32_dpp v194, v150 row_ror:1 row_mask:0xf bank_mask:0xf
	v_mov_b32_dpp v198, v150 row_ror:2 row_mask:0xf bank_mask:0xf
	v_mov_b32_dpp v195, v151 row_ror:1 row_mask:0xf bank_mask:0xf
	v_mov_b32_dpp v199, v151 row_ror:2 row_mask:0xf bank_mask:0xf
	v_mov_b32_dpp v196, v152 row_ror:1 row_mask:0xf bank_mask:0xf
	v_mov_b32_dpp v200, v152 row_ror:2 row_mask:0xf bank_mask:0xf
	v_mov_b32_dpp v197, v153 row_ror:1 row_mask:0xf bank_mask:0xf
	v_mov_b32_dpp v201, v153 row_ror:2 row_mask:0xf bank_mask:0xf
	s_nop 1
	v_mov_b32_dpp v194, v154 row_shr:1 row_mask:0xf bank_mask:0xf
	v_mov_b32_dpp v198, v154 row_shr:2 row_mask:0xf bank_mask:0xf
	v_mov_b32_dpp v195, v155 row_shr:1 row_mask:0xf bank_mask:0xf
	v_mov_b32_dpp v199, v155 row_shr:2 row_mask:0xf bank_mask:0xf
	v_mov_b32_dpp v196, v156 row_shr:1 row_mask:0xf bank_mask:0xf
	v_mov_b32_dpp v200, v156 row_shr:2 row_mask:0xf bank_mask:0xf
	v_mov_b32_dpp v197, v157 row_shr:1 row_mask:0xf bank_mask:0xf
	v_mov_b32_dpp v201, v157 row_shr:2 row_mask:0xf bank_mask:0xf
	v_pk_mul_f32 v[190:191], v[138:139], v[198:199]
	v_pk_mul_f32 v[192:193], v[140:141], v[200:201]
	v_pk_fma_f32 v[190:191], v[142:143], v[194:195], v[190:191]
	v_pk_fma_f32 v[192:193], v[144:145], v[196:197], v[192:193]
	v_pk_fma_f32 v[190:191], v[146:147], v[154:155], v[190:191]
	v_pk_fma_f32 v[192:193], v[148:149], v[156:157], v[192:193]
	v_pk_mul_f32 v[190:191], v[158:159], v[190:191]
	v_pk_mul_f32 v[192:193], v[160:161], v[192:193]
	v_cvt_pk_bf16_f32 v230, v190, v191
	v_cvt_pk_bf16_f32 v231, v192, v193
	global_store_dwordx2 v[204:205], v[230:231], off
	v_add_co_u32_e32 v204, vcc, 0x22000, v204
	s_nop 1
	v_addc_co_u32_e32 v205, vcc, 0, v205, vcc
	v_fmamk_f32 v202, v130, 0x3a800000, v209
	v_rsq_f32_e32 v202, v202
	v_pk_mul_f32 v[150:151], v[36:37], v[28:29]
	v_pk_mul_f32 v[152:153], v[38:39], v[30:31]
	v_mul_f32_e32 v206, v202, v202
	v_mul_f32_e32 v234, 0xbfb8aa3b, v202
	v_pk_mul_f32 v[158:159], v[8:9], v[202:203] op_sel_hi:[1,0]
	v_pk_mul_f32 v[160:161], v[10:11], v[202:203] op_sel_hi:[1,0]
	v_pk_mul_f32 v[150:151], v[150:151], v[206:207] op_sel_hi:[1,0]
	v_pk_mul_f32 v[152:153], v[152:153], v[206:207] op_sel_hi:[1,0]
	v_pk_mul_f32 v[162:163], v[8:9], v[234:235] op_sel_hi:[1,0]
	v_pk_mul_f32 v[164:165], v[10:11], v[234:235] op_sel_hi:[1,0]
	v_min_f32_e32 v162, 0x4266d4ca, v162
	v_min_f32_e32 v163, 0x4266d4ca, v163
	v_min_f32_e32 v164, 0x4266d4ca, v164
	v_min_f32_e32 v165, 0x4266d4ca, v165
	v_exp_f32_e32 v162, v162
	v_exp_f32_e32 v163, v163
	v_exp_f32_e32 v164, v164
	v_exp_f32_e32 v165, v165
	s_nop 0
	v_pk_add_f32 v[162:163], v[162:163], 1.0 op_sel_hi:[1,0]
	v_pk_add_f32 v[164:165], v[164:165], 1.0 op_sel_hi:[1,0]
	v_mul_f32_e32 v166, v162, v163
	v_mul_f32_e32 v167, v164, v165
	v_rcp_f32_e32 v166, v166
	v_rcp_f32_e32 v167, v167
	s_nop 0
	v_pk_mul_f32 v[162:163], v[162:163], v[166:167] op_sel:[1,0] op_sel_hi:[0,0]
	v_pk_mul_f32 v[164:165], v[164:165], v[166:167] op_sel:[1,1] op_sel_hi:[0,1]
	v_pk_mul_f32 v[158:159], v[158:159], v[162:163]
	v_pk_mul_f32 v[160:161], v[160:161], v[164:165]
	v_pk_mul_f32 v[162:163], v[16:17], v[202:203] op_sel_hi:[1,0]
;     __device__ __forceinline__ void operator()(const f32x4 (&acc)[2][2][4][2], const Unit& u, int wr, int wc, int fr, int fq, const LAS float* rsl) const {
;     ...
;                 } else if (pn < 17) {
;                     f32x4 b0 = acc[ai][0][m][0] * rstd, b1 = acc[ai][0][m][1] * rstd, z0 = acc[ai][1][m][0] * rstd, z1 = acc[ai][1][m][1] * rstd;
; #pragma unroll
;                     for (int j = 0; j < 4; ++j) { float sa, sb; sigmoid2(z0[j], z1[j], sa, sb); b0[j] *= z0[j] * sa; b1[j] *= z1[j] * sb; }
;                     store8bf_nt(rp + COL_BZ + (pn - 9) * 128, b0, b1);
;                 } else if (pn < 25) {
;                     const float r2 = rstd * rstd;
;                     store8bf_nt(rp + COL_HC + (pn - 17) * 128, acc[ai][0][m][0] * acc[ai][1][m][0] * r2, acc[ai][0][m][1] * acc[ai][1][m][1] * r2);
; __device__ void phase_scan_sc(KP P, int layer) {
;     ...
;         for (int i = 0; i < 16; ++i) { float h0[8], bz[8]; bf16_t* bp = proj + (rowS + i) * PW + COL_BZ + ch;
;             unpack8(__builtin_nontemporal_load((const u32x4*)(proj + (rowS + i) * PW + COL_HC + ch)), h0); unpack8(__builtin_nontemporal_load((const u32x4*)bp), bz);
;             float y[8];
; #pragma unroll
;             for (int j = 0; j < 8; ++j) { y[j] = bz[j] * (w0[j] * hm2[j] + w1[j] * hm1[j] + w2[j] * h0[j]); hm2[j] = hm1[j]; hm1[j] = h0[j]; }
;             *(u32x4*)bp = __builtin_bit_cast(u32x4, pack8(y)); }
	v_pk_mul_f32 v[164:165], v[18:19], v[202:203] op_sel_hi:[1,0]
	v_pk_mul_f32 v[158:159], v[162:163], v[158:159]
	v_pk_mul_f32 v[160:161], v[164:165], v[160:161]
	v_mov_b32_dpp v194, v154 row_ror:1 row_mask:0xf bank_mask:0xf
	v_mov_b32_dpp v198, v154 row_ror:2 row_mask:0xf bank_mask:0xf
	v_mov_b32_dpp v195, v155 row_ror:1 row_mask:0xf bank_mask:0xf
	v_mov_b32_dpp v199, v155 row_ror:2 row_mask:0xf bank_mask:0xf
	v_mov_b32_dpp v196, v156 row_ror:1 row_mask:0xf bank_mask:0xf
	v_mov_b32_dpp v200, v156 row_ror:2 row_mask:0xf bank_mask:0xf
	v_mov_b32_dpp v197, v157 row_ror:1 row_mask:0xf bank_mask:0xf
	v_mov_b32_dpp v201, v157 row_ror:2 row_mask:0xf bank_mask:0xf
	s_nop 1
	v_mov_b32_dpp v194, v150 row_shr:1 row_mask:0xf bank_mask:0xf
	v_mov_b32_dpp v198, v150 row_shr:2 row_mask:0xf bank_mask:0xf
	v_mov_b32_dpp v195, v151 row_shr:1 row_mask:0xf bank_mask:0xf
	v_mov_b32_dpp v199, v151 row_shr:2 row_mask:0xf bank_mask:0xf
	v_mov_b32_dpp v196, v152 row_shr:1 row_mask:0xf bank_mask:0xf
	v_mov_b32_dpp v200, v152 row_shr:2 row_mask:0xf bank_mask:0xf
	v_mov_b32_dpp v197, v153 row_shr:1 row_mask:0xf bank_mask:0xf
	v_mov_b32_dpp v201, v153 row_shr:2 row_mask:0xf bank_mask:0xf
	v_pk_mul_f32 v[190:191], v[138:139], v[198:199]
	v_pk_mul_f32 v[192:193], v[140:141], v[200:201]
	v_pk_fma_f32 v[190:191], v[142:143], v[194:195], v[190:191]
	v_pk_fma_f32 v[192:193], v[144:145], v[196:197], v[192:193]
	v_pk_fma_f32 v[190:191], v[146:147], v[150:151], v[190:191]
	v_pk_fma_f32 v[192:193], v[148:149], v[152:153], v[192:193]
	v_pk_mul_f32 v[190:191], v[158:159], v[190:191]
	v_pk_mul_f32 v[192:193], v[160:161], v[192:193]
	v_cvt_pk_bf16_f32 v230, v190, v191
	v_cvt_pk_bf16_f32 v231, v192, v193
	global_store_dwordx2 v[204:205], v[230:231], off
	v_add_co_u32_e32 v204, vcc, 0x22000, v204
	s_nop 1
	v_addc_co_u32_e32 v205, vcc, 0, v205, vcc
	v_fmamk_f32 v202, v131, 0x3a800000, v209
	v_rsq_f32_e32 v202, v202
	v_pk_mul_f32 v[154:155], v[20:21], v[12:13]
	v_pk_mul_f32 v[156:157], v[22:23], v[14:15]
	v_mul_f32_e32 v206, v202, v202
	v_mul_f32_e32 v234, 0xbfb8aa3b, v202
	v_pk_mul_f32 v[158:159], v[0:1], v[202:203] op_sel_hi:[1,0]
	v_pk_mul_f32 v[160:161], v[2:3], v[202:203] op_sel_hi:[1,0]
	v_pk_mul_f32 v[154:155], v[154:155], v[206:207] op_sel_hi:[1,0]
	v_pk_mul_f32 v[156:157], v[156:157], v[206:207] op_sel_hi:[1,0]
	v_pk_mul_f32 v[162:163], v[0:1], v[234:235] op_sel_hi:[1,0]
	v_pk_mul_f32 v[164:165], v[2:3], v[234:235] op_sel_hi:[1,0]
	v_min_f32_e32 v162, 0x4266d4ca, v162
	v_min_f32_e32 v163, 0x4266d4ca, v163
	v_min_f32_e32 v164, 0x4266d4ca, v164
	v_min_f32_e32 v165, 0x4266d4ca, v165
	v_exp_f32_e32 v162, v162
	v_exp_f32_e32 v163, v163
	v_exp_f32_e32 v164, v164
	v_exp_f32_e32 v165, v165
	s_nop 0
	v_pk_add_f32 v[162:163], v[162:163], 1.0 op_sel_hi:[1,0]
	v_pk_add_f32 v[164:165], v[164:165], 1.0 op_sel_hi:[1,0]
	v_mul_f32_e32 v166, v162, v163
	v_mul_f32_e32 v167, v164, v165
	v_rcp_f32_e32 v166, v166
	v_rcp_f32_e32 v167, v167
	s_nop 0
	v_pk_mul_f32 v[162:163], v[162:163], v[166:167] op_sel:[1,0] op_sel_hi:[0,0]
	v_pk_mul_f32 v[164:165], v[164:165], v[166:167] op_sel:[1,1] op_sel_hi:[0,1]
	v_pk_mul_f32 v[158:159], v[158:159], v[162:163]
	v_pk_mul_f32 v[160:161], v[160:161], v[164:165]
	v_pk_mul_f32 v[162:163], v[4:5], v[202:203] op_sel_hi:[1,0]
	v_pk_mul_f32 v[164:165], v[6:7], v[202:203] op_sel_hi:[1,0]
	v_pk_mul_f32 v[158:159], v[162:163], v[158:159]
	v_pk_mul_f32 v[160:161], v[164:165], v[160:161]
	v_mov_b32_dpp v194, v150 row_ror:1 row_mask:0xf bank_mask:0xf
	v_mov_b32_dpp v198, v150 row_ror:2 row_mask:0xf bank_mask:0xf
	v_mov_b32_dpp v195, v151 row_ror:1 row_mask:0xf bank_mask:0xf
	v_mov_b32_dpp v199, v151 row_ror:2 row_mask:0xf bank_mask:0xf
	v_mov_b32_dpp v196, v152 row_ror:1 row_mask:0xf bank_mask:0xf
	v_mov_b32_dpp v200, v152 row_ror:2 row_mask:0xf bank_mask:0xf
	v_mov_b32_dpp v197, v153 row_ror:1 row_mask:0xf bank_mask:0xf
	v_mov_b32_dpp v201, v153 row_ror:2 row_mask:0xf bank_mask:0xf
	s_nop 1
	v_mov_b32_dpp v194, v154 row_shr:1 row_mask:0xf bank_mask:0xf
	v_mov_b32_dpp v198, v154 row_shr:2 row_mask:0xf bank_mask:0xf
	v_mov_b32_dpp v195, v155 row_shr:1 row_mask:0xf bank_mask:0xf
	v_mov_b32_dpp v199, v155 row_shr:2 row_mask:0xf bank_mask:0xf
	v_mov_b32_dpp v196, v156 row_shr:1 row_mask:0xf bank_mask:0xf
	v_mov_b32_dpp v200, v156 row_shr:2 row_mask:0xf bank_mask:0xf
	v_mov_b32_dpp v197, v157 row_shr:1 row_mask:0xf bank_mask:0xf
	v_mov_b32_dpp v201, v157 row_shr:2 row_mask:0xf bank_mask:0xf
	v_pk_mul_f32 v[190:191], v[138:139], v[198:199]
	v_pk_mul_f32 v[192:193], v[140:141], v[200:201]
	v_pk_fma_f32 v[190:191], v[142:143], v[194:195], v[190:191]
	v_pk_fma_f32 v[192:193], v[144:145], v[196:197], v[192:193]
	v_pk_fma_f32 v[190:191], v[146:147], v[154:155], v[190:191]
	v_pk_fma_f32 v[192:193], v[148:149], v[156:157], v[192:193]
	v_pk_mul_f32 v[190:191], v[158:159], v[190:191]
	v_pk_mul_f32 v[192:193], v[160:161], v[192:193]
	v_cvt_pk_bf16_f32 v230, v190, v191
	v_cvt_pk_bf16_f32 v231, v192, v193
	global_store_dwordx2 v[204:205], v[230:231], off
	v_cvt_pk_bf16_f32 v232, v154, v155
	v_cvt_pk_bf16_f32 v233, v156, v157
	s_mov_b64 exec, s[72:73]
	global_store_dwordx2 v[204:205], v[232:233], off offset:2048
	s_mov_b64 exec, -1
	s_branch .LBB0_351
